# v21 + P6 chunk-state scans: next batch's 16 addresses touched by throw-away loads right after each batch's loads (software prefetch), vmcnt counts +16
# speedup vs baseline: 1.0011x; 1.0011x over previous
; __device__ __forceinline__ float bflo(unsigned w) { return __uint_as_float(w << 16); }
; __device__ __forceinline__ float bfhi(unsigned w) { return __uint_as_float(w & 0xffff0000u); }
; __device__ __forceinline__ unsigned pk2(float lo, float hi) { f32x2 v = {lo, hi}; bf16x2_t b = __builtin_convertvector(v, bf16x2_t); return __builtin_bit_cast(unsigned, b); }
; __device__ __forceinline__ void mlstm_passB8(const float* UL, const float* NL, const float* SC, bf16* CST, float* NS, float* MS, int t, int nthreads, LAS f32x2* tabw, int lane) {
;     ...
;         for (int cb = 0; cb < NCH; cb += SCAN_BATCH) {
;             unsigned u[SCAN_BATCH];
; #pragma unroll
;             for (int j = 0; j < SCAN_BATCH; ++j) u[j] = *(const unsigned*)((const bf16*)UL + (size_t)(h * NCH + cb + j) * (DV * DK) + e);
; #pragma unroll
;             for (int j = 0; j < SCAN_BATCH; ++j) { const int c = cb + j; const f32x2 ab = tabw[c];
;                 *(unsigned*)(CST + (size_t)(h * NCH + c) * (DV * DK) + e) = pk2(cc.x, cc.y);
;                 cc = cc * ab.x + (f32x2){bflo(u[j]), bfhi(u[j])} * ab.y; }
;         }
.LBB0_523:
	v_add_co_u32_e32 v4, vcc, 0xfff10000, v10
	v_mov_b32_e32 v33, s15
	s_nop 0
	v_addc_co_u32_e32 v5, vcc, -1, v11, vcc
	global_load_dword v34, v[4:5], off
	v_add_co_u32_e32 v4, vcc, 0xfff20000, v10
	v_cvt_pk_bf16_f32 v36, v2, v3
	s_nop 0
	v_addc_co_u32_e32 v5, vcc, -1, v11, vcc
	global_load_dword v35, v[4:5], off
	v_add_co_u32_e32 v4, vcc, 0xfff30000, v10
	s_mov_b32 s26, 0xfbf30000
	s_nop 0
	v_addc_co_u32_e32 v5, vcc, -1, v11, vcc
	global_load_dword v46, v[4:5], off
	v_add_co_u32_e32 v4, vcc, 0xfff40000, v10
	s_add_i32 s14, s14, 16
	s_nop 0
	v_addc_co_u32_e32 v5, vcc, -1, v11, vcc
	global_load_dword v47, v[4:5], off
	v_add_co_u32_e32 v4, vcc, 0xfff50000, v10
	s_addk_i32 s15, 0x80
	s_nop 0
	v_addc_co_u32_e32 v5, vcc, -1, v11, vcc
	global_load_dword v48, v[4:5], off
	v_add_co_u32_e32 v4, vcc, 0xfff60000, v10
	s_cmpk_lt_u32 s14, 0x70
	s_nop 0
	v_addc_co_u32_e32 v5, vcc, -1, v11, vcc
	global_load_dword v32, v[4:5], off
	v_add_co_u32_e32 v4, vcc, 0xfff70000, v10
	s_nop 1
	v_addc_co_u32_e32 v5, vcc, -1, v11, vcc
	global_load_dword v31, v[4:5], off
	v_add_co_u32_e32 v4, vcc, 0xfff80000, v10
	s_nop 1
	v_addc_co_u32_e32 v5, vcc, -1, v11, vcc
	global_load_dword v30, v[4:5], off
	v_add_co_u32_e32 v4, vcc, 0xfff90000, v10
	s_nop 1
	v_addc_co_u32_e32 v5, vcc, -1, v11, vcc
	global_load_dword v29, v[4:5], off
	v_add_co_u32_e32 v4, vcc, 0xfffa0000, v10
	s_nop 1
	v_addc_co_u32_e32 v5, vcc, -1, v11, vcc
	global_load_dword v27, v[4:5], off
	v_add_co_u32_e32 v4, vcc, 0xfffb0000, v10
	s_nop 1
	v_addc_co_u32_e32 v5, vcc, -1, v11, vcc
	global_load_dword v26, v[4:5], off
	v_add_co_u32_e32 v4, vcc, 0xfffc0000, v10
	s_nop 1
	v_addc_co_u32_e32 v5, vcc, -1, v11, vcc
	global_load_dword v15, v[4:5], off
	v_add_co_u32_e32 v4, vcc, 0xfffd0000, v10
	s_nop 1
	v_addc_co_u32_e32 v5, vcc, -1, v11, vcc
	global_load_dword v14, v[4:5], off
	v_add_co_u32_e32 v4, vcc, 0xfffe0000, v10
	s_nop 1
	v_addc_co_u32_e32 v5, vcc, -1, v11, vcc
	global_load_dword v13, v[4:5], off
	v_add_co_u32_e32 v4, vcc, 0xffff0000, v10
	s_nop 1
	v_addc_co_u32_e32 v5, vcc, -1, v11, vcc
	global_load_dword v12, v[4:5], off
	global_load_dword v28, v[10:11], off
	v_lshl_add_u64 v[240:241], v[10:11], 0, s[74:75]
	v_add_co_u32_e32 v242, vcc, 0xfff10000, v240
	s_nop 1
	v_addc_co_u32_e32 v243, vcc, -1, v241, vcc
	global_load_dword v244, v[242:243], off
	v_add_co_u32_e32 v242, vcc, 0xfff20000, v240
	s_nop 1
	v_addc_co_u32_e32 v243, vcc, -1, v241, vcc
	global_load_dword v244, v[242:243], off
	v_add_co_u32_e32 v242, vcc, 0xfff30000, v240
	s_nop 1
	v_addc_co_u32_e32 v243, vcc, -1, v241, vcc
	global_load_dword v244, v[242:243], off
	v_add_co_u32_e32 v242, vcc, 0xfff40000, v240
	s_nop 1
	v_addc_co_u32_e32 v243, vcc, -1, v241, vcc
	global_load_dword v244, v[242:243], off
	v_add_co_u32_e32 v242, vcc, 0xfff50000, v240
	s_nop 1
	v_addc_co_u32_e32 v243, vcc, -1, v241, vcc
	global_load_dword v244, v[242:243], off
	v_add_co_u32_e32 v242, vcc, 0xfff60000, v240
	s_nop 1
	v_addc_co_u32_e32 v243, vcc, -1, v241, vcc
	global_load_dword v244, v[242:243], off
	v_add_co_u32_e32 v242, vcc, 0xfff70000, v240
	s_nop 1
	v_addc_co_u32_e32 v243, vcc, -1, v241, vcc
	global_load_dword v244, v[242:243], off
	v_add_co_u32_e32 v242, vcc, 0xfff80000, v240
	s_nop 1
	v_addc_co_u32_e32 v243, vcc, -1, v241, vcc
	global_load_dword v244, v[242:243], off
	v_add_co_u32_e32 v242, vcc, 0xfff90000, v240
	s_nop 1
	v_addc_co_u32_e32 v243, vcc, -1, v241, vcc
	global_load_dword v244, v[242:243], off
	v_add_co_u32_e32 v242, vcc, 0xfffa0000, v240
	s_nop 1
	v_addc_co_u32_e32 v243, vcc, -1, v241, vcc
	global_load_dword v244, v[242:243], off
	v_add_co_u32_e32 v242, vcc, 0xfffb0000, v240
	s_nop 1
	v_addc_co_u32_e32 v243, vcc, -1, v241, vcc
	global_load_dword v244, v[242:243], off
	v_add_co_u32_e32 v242, vcc, 0xfffc0000, v240
	s_nop 1
	v_addc_co_u32_e32 v243, vcc, -1, v241, vcc
	global_load_dword v244, v[242:243], off
	v_add_co_u32_e32 v242, vcc, 0xfffd0000, v240
	s_nop 1
	v_addc_co_u32_e32 v243, vcc, -1, v241, vcc
	global_load_dword v244, v[242:243], off
	v_add_co_u32_e32 v242, vcc, 0xfffe0000, v240
	s_nop 1
	v_addc_co_u32_e32 v243, vcc, -1, v241, vcc
	global_load_dword v244, v[242:243], off
	v_add_co_u32_e32 v242, vcc, 0xffff0000, v240
	s_nop 1
	v_addc_co_u32_e32 v243, vcc, -1, v241, vcc
	global_load_dword v244, v[242:243], off
	global_load_dword v244, v[240:241], off
	ds_read_b128 v[4:7], v33
	v_add_co_u32_e32 v8, vcc, 0xfbf10000, v10
	s_nop 1
	v_addc_co_u32_e32 v9, vcc, -1, v11, vcc
	global_store_dword v[8:9], v36, off
	s_waitcnt vmcnt(32)
	v_lshlrev_b32_e32 v8, 16, v34
	v_and_b32_e32 v9, 0xffff0000, v34
	s_waitcnt lgkmcnt(0)
	v_pk_mul_f32 v[8:9], v[4:5], v[8:9] op_sel:[1,0]
	s_nop 0
	v_pk_fma_f32 v[2:3], v[2:3], v[4:5], v[8:9] op_sel_hi:[1,0,1]
	v_add_co_u32_e32 v4, vcc, 0xfbf20000, v10
	v_cvt_pk_bf16_f32 v8, v2, v3
	s_nop 0
	v_addc_co_u32_e32 v5, vcc, -1, v11, vcc
	global_store_dword v[4:5], v8, off
	s_waitcnt vmcnt(32)
	v_lshlrev_b32_e32 v4, 16, v35
	v_and_b32_e32 v5, 0xffff0000, v35
	v_mov_b32_e32 v8, v7
	v_pk_mul_f32 v[4:5], v[8:9], v[4:5] op_sel_hi:[0,1]
	v_pk_fma_f32 v[42:43], v[2:3], v[6:7], v[4:5] op_sel_hi:[1,0,1]
	v_add_co_u32_e32 v44, vcc, s26, v10
	ds_read_b128 v[34:37], v33 offset:16
	ds_read_b128 v[38:41], v33 offset:32
	ds_read_b128 v[6:9], v33 offset:48
	ds_read_b128 v[2:5], v33 offset:64
	v_cvt_pk_bf16_f32 v49, v42, v43
	v_addc_co_u32_e32 v45, vcc, -1, v11, vcc
	global_store_dword v[44:45], v49, off
	s_waitcnt vmcnt(32)
	v_lshlrev_b32_e32 v44, 16, v46
	v_and_b32_e32 v45, 0xffff0000, v46
	s_waitcnt lgkmcnt(3)
; __device__ __forceinline__ float bflo(unsigned w) { return __uint_as_float(w << 16); }
; __device__ __forceinline__ float bfhi(unsigned w) { return __uint_as_float(w & 0xffff0000u); }
; __device__ __forceinline__ unsigned pk2(float lo, float hi) { f32x2 v = {lo, hi}; bf16x2_t b = __builtin_convertvector(v, bf16x2_t); return __builtin_bit_cast(unsigned, b); }
; __device__ __forceinline__ void mlstm_passB8(const float* UL, const float* NL, const float* SC, bf16* CST, float* NS, float* MS, int t, int nthreads, LAS f32x2* tabw, int lane) {
;     ...
;     for (int p = t; p < MLH * PER_HEAD; p += nthreads) {
;         const int h = __builtin_amdgcn_readfirstlane(p / PER_HEAD), e = (p % PER_HEAD) * 2;
;         scan_table(SC, h, tabw, ((p - lane) % PER_HEAD) == 0 ? MS : nullptr, lane);
;         f32x2 cc = {0.f, 0.f};
;         for (int cb = 0; cb < NCH; cb += SCAN_BATCH) {
;             unsigned u[SCAN_BATCH];
; #pragma unroll
;             for (int j = 0; j < SCAN_BATCH; ++j) u[j] = *(const unsigned*)((const bf16*)UL + (size_t)(h * NCH + cb + j) * (DV * DK) + e);
; #pragma unroll
;             for (int j = 0; j < SCAN_BATCH; ++j) { const int c = cb + j; const f32x2 ab = tabw[c];
;                 *(unsigned*)(CST + (size_t)(h * NCH + c) * (DV * DK) + e) = pk2(cc.x, cc.y);
;                 cc = cc * ab.x + (f32x2){bflo(u[j]), bfhi(u[j])} * ab.y; }
;         }
	v_pk_mul_f32 v[44:45], v[34:35], v[44:45] op_sel:[1,0]
	s_mov_b32 s26, 0xfbf40000
	v_pk_fma_f32 v[34:35], v[42:43], v[34:35], v[44:45] op_sel_hi:[1,0,1]
	v_add_co_u32_e32 v42, vcc, s26, v10
	v_cvt_pk_bf16_f32 v44, v34, v35
	s_nop 0
	v_addc_co_u32_e32 v43, vcc, -1, v11, vcc
	global_store_dword v[42:43], v44, off
	s_waitcnt vmcnt(32)
	v_lshlrev_b32_e32 v42, 16, v47
	v_and_b32_e32 v43, 0xffff0000, v47
	v_mov_b32_e32 v44, v37
	v_pk_mul_f32 v[42:43], v[44:45], v[42:43] op_sel_hi:[0,1]
	s_mov_b32 s26, 0xfbf50000
	v_pk_fma_f32 v[34:35], v[34:35], v[36:37], v[42:43] op_sel_hi:[1,0,1]
	v_add_co_u32_e32 v36, vcc, s26, v10
	v_cvt_pk_bf16_f32 v42, v34, v35
	s_nop 0
	v_addc_co_u32_e32 v37, vcc, -1, v11, vcc
	global_store_dword v[36:37], v42, off
	s_waitcnt vmcnt(32)
	v_lshlrev_b32_e32 v36, 16, v48
	v_and_b32_e32 v37, 0xffff0000, v48
	s_waitcnt lgkmcnt(2)
	v_pk_mul_f32 v[36:37], v[38:39], v[36:37] op_sel:[1,0]
	s_mov_b32 s26, 0xfbf60000
	v_pk_fma_f32 v[34:35], v[34:35], v[38:39], v[36:37] op_sel_hi:[1,0,1]
	v_add_co_u32_e32 v36, vcc, s26, v10
	v_cvt_pk_bf16_f32 v38, v34, v35
	s_nop 0
	v_addc_co_u32_e32 v37, vcc, -1, v11, vcc
	global_store_dword v[36:37], v38, off
	s_waitcnt vmcnt(32)
	v_lshlrev_b32_e32 v36, 16, v32
	v_and_b32_e32 v37, 0xffff0000, v32
	v_mov_b32_e32 v32, v41
	v_pk_mul_f32 v[36:37], v[32:33], v[36:37] op_sel_hi:[0,1]
	v_pk_fma_f32 v[34:35], v[34:35], v[40:41], v[36:37] op_sel_hi:[1,0,1]
	v_add_co_u32_e32 v36, vcc, s61, v10
	v_cvt_pk_bf16_f32 v32, v34, v35
	s_nop 0
	v_addc_co_u32_e32 v37, vcc, -1, v11, vcc
	global_store_dword v[36:37], v32, off
	s_waitcnt vmcnt(32)
	v_lshlrev_b32_e32 v36, 16, v31
	v_and_b32_e32 v37, 0xffff0000, v31
	s_waitcnt lgkmcnt(1)
	v_pk_mul_f32 v[36:37], v[6:7], v[36:37] op_sel:[1,0]
	s_nop 0
	v_pk_fma_f32 v[6:7], v[34:35], v[6:7], v[36:37] op_sel_hi:[1,0,1]
	v_add_co_u32_e32 v34, vcc, s78, v10
	v_cvt_pk_bf16_f32 v31, v6, v7
	s_nop 0
	v_addc_co_u32_e32 v35, vcc, -1, v11, vcc
	global_store_dword v[34:35], v31, off
	s_waitcnt vmcnt(32)
	v_lshlrev_b32_e32 v34, 16, v30
	v_and_b32_e32 v35, 0xffff0000, v30
	v_mov_b32_e32 v30, v9
	v_pk_mul_f32 v[30:31], v[30:31], v[34:35] op_sel_hi:[0,1]
	v_pk_fma_f32 v[6:7], v[6:7], v[8:9], v[30:31] op_sel_hi:[1,0,1]
	v_add_co_u32_e32 v8, vcc, s79, v10
	v_cvt_pk_bf16_f32 v30, v6, v7
	s_nop 0
	v_addc_co_u32_e32 v9, vcc, -1, v11, vcc
	global_store_dword v[8:9], v30, off
	s_waitcnt vmcnt(32)
	v_lshlrev_b32_e32 v8, 16, v29
	v_and_b32_e32 v9, 0xffff0000, v29
	s_waitcnt lgkmcnt(0)
	v_pk_mul_f32 v[8:9], v[2:3], v[8:9] op_sel:[1,0]
	s_nop 0
	v_pk_fma_f32 v[2:3], v[6:7], v[2:3], v[8:9] op_sel_hi:[1,0,1]
	v_add_co_u32_e32 v6, vcc, s80, v10
	v_cvt_pk_bf16_f32 v8, v2, v3
	s_nop 0
	v_addc_co_u32_e32 v7, vcc, -1, v11, vcc
	global_store_dword v[6:7], v8, off
	s_waitcnt vmcnt(32)
	v_lshlrev_b32_e32 v6, 16, v27
	v_and_b32_e32 v7, 0xffff0000, v27
	v_mov_b32_e32 v8, v5
	v_pk_mul_f32 v[6:7], v[8:9], v[6:7] op_sel_hi:[0,1]
	v_pk_fma_f32 v[6:7], v[2:3], v[4:5], v[6:7] op_sel_hi:[1,0,1]
	ds_read_b128 v[2:5], v33 offset:80
	v_add_co_u32_e32 v8, vcc, s81, v10
	v_cvt_pk_bf16_f32 v27, v6, v7
	s_nop 0
	v_addc_co_u32_e32 v9, vcc, -1, v11, vcc
	global_store_dword v[8:9], v27, off
	s_waitcnt vmcnt(32)
	v_lshlrev_b32_e32 v8, 16, v26
	v_and_b32_e32 v9, 0xffff0000, v26
	s_waitcnt lgkmcnt(0)
	v_pk_mul_f32 v[8:9], v[2:3], v[8:9] op_sel:[1,0]
	s_nop 0
	v_pk_fma_f32 v[2:3], v[6:7], v[2:3], v[8:9] op_sel_hi:[1,0,1]
	v_add_co_u32_e32 v6, vcc, s82, v10
	v_cvt_pk_bf16_f32 v8, v2, v3
	s_nop 0
	v_addc_co_u32_e32 v7, vcc, -1, v11, vcc
	global_store_dword v[6:7], v8, off
	s_waitcnt vmcnt(32)
	v_lshlrev_b32_e32 v6, 16, v15
	v_and_b32_e32 v7, 0xffff0000, v15
	v_mov_b32_e32 v8, v5
	v_pk_mul_f32 v[6:7], v[8:9], v[6:7] op_sel_hi:[0,1]
	v_pk_fma_f32 v[26:27], v[2:3], v[4:5], v[6:7] op_sel_hi:[1,0,1]
	ds_read_b128 v[2:5], v33 offset:96
	ds_read_b128 v[6:9], v33 offset:112
	v_add_co_u32_e32 v30, vcc, s83, v10
	v_cvt_pk_bf16_f32 v15, v26, v27
	s_nop 0
	v_addc_co_u32_e32 v31, vcc, -1, v11, vcc
	global_store_dword v[30:31], v15, off
	s_waitcnt vmcnt(32)
	v_lshlrev_b32_e32 v30, 16, v14
	v_and_b32_e32 v31, 0xffff0000, v14
	s_waitcnt lgkmcnt(1)
	v_pk_mul_f32 v[14:15], v[2:3], v[30:31] op_sel:[1,0]
	s_nop 0
	v_pk_fma_f32 v[2:3], v[26:27], v[2:3], v[14:15] op_sel_hi:[1,0,1]
	v_add_co_u32_e32 v14, vcc, s62, v10
	v_cvt_pk_bf16_f32 v26, v2, v3
	s_nop 0
	v_addc_co_u32_e32 v15, vcc, -1, v11, vcc
	global_store_dword v[14:15], v26, off
	s_waitcnt vmcnt(32)
	v_lshlrev_b32_e32 v14, 16, v13
	v_and_b32_e32 v15, 0xffff0000, v13
	v_mov_b32_e32 v26, v5
	v_pk_mul_f32 v[14:15], v[26:27], v[14:15] op_sel_hi:[0,1]
	v_pk_fma_f32 v[2:3], v[2:3], v[4:5], v[14:15] op_sel_hi:[1,0,1]
	v_add_co_u32_e32 v4, vcc, s63, v10
	v_cvt_pk_bf16_f32 v13, v2, v3
	s_nop 0
	v_addc_co_u32_e32 v5, vcc, -1, v11, vcc
	global_store_dword v[4:5], v13, off
	s_waitcnt vmcnt(32)
	v_lshlrev_b32_e32 v4, 16, v12
	v_and_b32_e32 v5, 0xffff0000, v12
	s_waitcnt lgkmcnt(0)
	v_pk_mul_f32 v[4:5], v[6:7], v[4:5] op_sel:[1,0]
	s_nop 0
	v_pk_fma_f32 v[2:3], v[2:3], v[6:7], v[4:5] op_sel_hi:[1,0,1]
	v_add_co_u32_e32 v4, vcc, s84, v10
	v_cvt_pk_bf16_f32 v6, v2, v3
	s_nop 0
	v_addc_co_u32_e32 v5, vcc, -1, v11, vcc
	global_store_dword v[4:5], v6, off
	s_waitcnt vmcnt(32)
	v_lshlrev_b32_e32 v4, 16, v28
	v_and_b32_e32 v5, 0xffff0000, v28
	v_mov_b32_e32 v6, v9
	v_pk_mul_f32 v[4:5], v[6:7], v[4:5] op_sel_hi:[0,1]
	v_pk_fma_f32 v[2:3], v[2:3], v[8:9], v[4:5] op_sel_hi:[1,0,1]
	v_lshl_add_u64 v[10:11], v[10:11], 0, s[74:75]
	s_cbranch_scc1 .LBB0_523
	v_add_u32_e32 v25, s3, v25
	v_cmp_lt_i32_e32 vcc, s85, v25
	s_or_b64 s[72:73], vcc, s[72:73]
	s_andn2_b64 exec, exec, s[72:73]
	s_cbranch_execnz .LBB0_520

; __device__ __forceinline__ void mlstm_passB8(const float* UL, const float* NL, const float* SC, bf16* CST, float* NS, float* MS, int t, int nthreads, LAS f32x2* tabw, int lane) {
;     ...
;     for (int p = t; p < MLH * DK; p += nthreads) {
;         const int h = __builtin_amdgcn_readfirstlane(p >> 7), dk = p & 127; float n = 0.f;
;         scan_table(SC, h, tabw, nullptr, lane);
;         for (int cb = 0; cb < NCH; cb += SCAN_BATCH) {
;             float u[SCAN_BATCH];
; #pragma unroll
;             for (int j = 0; j < SCAN_BATCH; ++j) u[j] = NL[(size_t)(h * NCH + cb + j) * DK + dk];
; #pragma unroll
;             for (int j = 0; j < SCAN_BATCH; ++j) { const int c = cb + j; const f32x2 ab = tabw[c]; NS[(size_t)(h * NCH + c) * DK + dk] = n; n = ab.x * n + ab.y * u[j]; }
;         }
.LBB0_528:
	v_add_co_u32_e32 v8, vcc, 0xffeff000, v4
	s_add_i32 s35, s35, 16
	s_nop 0
	v_addc_co_u32_e32 v9, vcc, -1, v5, vcc
	global_load_dword v7, v[8:9], off offset:-3584
	global_load_dword v19, v[8:9], off offset:-3072
	global_load_dword v53, v[8:9], off offset:-2560
	global_load_dword v55, v[8:9], off offset:-2048
	global_load_dword v57, v[8:9], off offset:-1536
	global_load_dword v59, v[8:9], off offset:-1024
	global_load_dword v61, v[8:9], off offset:-512
	global_load_dword v63, v[8:9], off
	v_add_co_u32_e32 v8, vcc, 0xfff00000, v4
	s_nop 1
	v_addc_co_u32_e32 v9, vcc, -1, v5, vcc
	global_load_dword v65, v[8:9], off offset:-3584
	global_load_dword v67, v[8:9], off offset:-3072
	global_load_dword v69, v[8:9], off offset:-2560
	global_load_dword v71, v[8:9], off offset:-2048
	global_load_dword v73, v[8:9], off offset:-1536
	global_load_dword v75, v[8:9], off offset:-1024
	global_load_dword v76, v[8:9], off offset:-512
	global_load_dword v77, v[8:9], off
	v_lshl_add_u64 v[240:241], v[4:5], 0, s[70:71]
	v_add_co_u32_e32 v242, vcc, 0xffeff000, v240
	s_nop 1
	v_addc_co_u32_e32 v243, vcc, -1, v241, vcc
	global_load_dword v244, v[242:243], off offset:-3584
	global_load_dword v244, v[242:243], off offset:-3072
	global_load_dword v244, v[242:243], off offset:-2560
	global_load_dword v244, v[242:243], off offset:-2048
	global_load_dword v244, v[242:243], off offset:-1536
	global_load_dword v244, v[242:243], off offset:-1024
	global_load_dword v244, v[242:243], off offset:-512
	global_load_dword v244, v[242:243], off
	v_add_co_u32_e32 v242, vcc, 0xfff00000, v240
	s_nop 1
	v_addc_co_u32_e32 v243, vcc, -1, v241, vcc
	global_load_dword v244, v[242:243], off offset:-3584
	global_load_dword v244, v[242:243], off offset:-3072
	global_load_dword v244, v[242:243], off offset:-2560
	global_load_dword v244, v[242:243], off offset:-2048
	global_load_dword v244, v[242:243], off offset:-1536
	global_load_dword v244, v[242:243], off offset:-1024
	global_load_dword v244, v[242:243], off offset:-512
	global_load_dword v244, v[242:243], off
	v_mov_b32_e32 v8, s33
	ds_read_b128 v[20:23], v8
	ds_read_b128 v[24:27], v8 offset:16
	ds_read_b128 v[28:31], v8 offset:32
	ds_read_b128 v[32:35], v8 offset:48
	ds_read_b128 v[36:39], v8 offset:64
	ds_read_b128 v[40:43], v8 offset:80
	ds_read_b128 v[44:47], v8 offset:96
	ds_read_b128 v[48:51], v8 offset:112
	v_add_co_u32_e32 v8, vcc, s30, v4
	s_addk_i32 s33, 0x80
	s_nop 0
	v_addc_co_u32_e32 v9, vcc, -1, v5, vcc
	global_store_dword v[8:9], v6, off offset:-3584
	s_cmpk_lt_u32 s35, 0x70
	s_waitcnt vmcnt(32) lgkmcnt(7)
	v_mul_f32_e32 v52, v7, v21
	s_waitcnt vmcnt(31)
	v_mul_f32_e32 v54, v19, v23
	s_waitcnt vmcnt(30)
	v_pk_fma_f32 v[6:7], v[6:7], v[20:21], v[52:53] op_sel_hi:[1,1,0]
	global_store_dword v[8:9], v6, off offset:-3072
	v_mov_b32_e32 v7, v19
	s_waitcnt vmcnt(30)
	v_pk_fma_f32 v[6:7], v[6:7], v[22:23], v[54:55] op_sel_hi:[1,1,0]
	s_waitcnt lgkmcnt(6)
	v_mul_f32_e32 v56, v53, v25
	v_mov_b32_e32 v7, v53
	global_store_dword v[8:9], v6, off offset:-2560
	s_waitcnt vmcnt(30)
	v_pk_fma_f32 v[6:7], v[6:7], v[24:25], v[56:57] op_sel_hi:[1,1,0]
	v_mul_f32_e32 v58, v55, v27
	v_mov_b32_e32 v7, v55
	global_store_dword v[8:9], v6, off offset:-2048
	s_waitcnt vmcnt(30)
	v_pk_fma_f32 v[6:7], v[6:7], v[26:27], v[58:59] op_sel_hi:[1,1,0]
	s_waitcnt lgkmcnt(5)
	v_mul_f32_e32 v60, v57, v29
	v_mov_b32_e32 v7, v57
	global_store_dword v[8:9], v6, off offset:-1536
	s_waitcnt vmcnt(30)
	v_pk_fma_f32 v[6:7], v[6:7], v[28:29], v[60:61] op_sel_hi:[1,1,0]
	v_mul_f32_e32 v62, v59, v31
	v_mov_b32_e32 v7, v59
	global_store_dword v[8:9], v6, off offset:-1024
	s_waitcnt vmcnt(30)
	v_pk_fma_f32 v[6:7], v[6:7], v[30:31], v[62:63] op_sel_hi:[1,1,0]
	s_waitcnt lgkmcnt(4)
	v_mul_f32_e32 v64, v61, v33
	v_mov_b32_e32 v7, v61
	global_store_dword v[8:9], v6, off offset:-512
	s_waitcnt vmcnt(30)
	v_pk_fma_f32 v[6:7], v[6:7], v[32:33], v[64:65] op_sel_hi:[1,1,0]
	v_mul_f32_e32 v66, v63, v35
	v_mov_b32_e32 v7, v63
	global_store_dword v[4:5], v6, off offset:-4096
	s_waitcnt vmcnt(30)
	v_pk_fma_f32 v[6:7], v[6:7], v[34:35], v[66:67] op_sel_hi:[1,1,0]
	s_waitcnt lgkmcnt(3)
	v_mul_f32_e32 v20, v65, v37
	v_mov_b32_e32 v7, v65
	global_store_dword v[4:5], v6, off offset:-3584
	v_pk_fma_f32 v[6:7], v[6:7], v[36:37], v[20:21] op_sel_hi:[1,1,0]
	v_mul_f32_e32 v52, v67, v39
	v_mov_b32_e32 v7, v67
	global_store_dword v[4:5], v6, off offset:-3072
	v_pk_fma_f32 v[6:7], v[6:7], v[38:39], v[52:53] op_sel_hi:[1,1,0]
	s_waitcnt vmcnt(31) lgkmcnt(2)
	v_mul_f32_e32 v68, v69, v41
	v_mov_b32_e32 v7, v69
	global_store_dword v[4:5], v6, off offset:-2560
	v_pk_fma_f32 v[6:7], v[6:7], v[40:41], v[68:69] op_sel_hi:[1,1,0]
	s_waitcnt vmcnt(31)
	v_mul_f32_e32 v70, v71, v43
	v_mov_b32_e32 v7, v71
	global_store_dword v[4:5], v6, off offset:-2048
	v_pk_fma_f32 v[6:7], v[6:7], v[42:43], v[70:71] op_sel_hi:[1,1,0]
	s_waitcnt vmcnt(31) lgkmcnt(1)
	v_mul_f32_e32 v72, v73, v45
	v_mov_b32_e32 v7, v73
	global_store_dword v[4:5], v6, off offset:-1536
	v_pk_fma_f32 v[6:7], v[6:7], v[44:45], v[72:73] op_sel_hi:[1,1,0]
	s_waitcnt vmcnt(31)
	v_mul_f32_e32 v74, v75, v47
	v_mov_b32_e32 v7, v75
	global_store_dword v[4:5], v6, off offset:-1024
	v_pk_fma_f32 v[6:7], v[6:7], v[46:47], v[74:75] op_sel_hi:[1,1,0]
	global_store_dword v[4:5], v6, off offset:-512
	s_waitcnt vmcnt(32)
	v_mov_b32_e32 v7, v76
	s_waitcnt lgkmcnt(0)
	v_pk_mul_f32 v[6:7], v[6:7], v[48:49]
	s_nop 0
	v_add_f32_e32 v6, v6, v7
	global_store_dword v[4:5], v6, off
	v_mul_f32_e32 v6, v6, v50
	s_waitcnt vmcnt(32)
	v_fmac_f32_e32 v6, v77, v51
	v_lshl_add_u64 v[4:5], v[4:5], 0, s[70:71]
	s_cbranch_scc1 .LBB0_528
	v_add_u32_e32 v1, s3, v1
	v_cmp_lt_i32_e32 vcc, s31, v1
	s_or_b64 s[16:17], vcc, s[16:17]
	s_andn2_b64 exec, exec, s[16:17]
	s_cbranch_execnz .LBB0_527
